# v21 + rpb table load batched (one wait) + in-proj epilogue fast path for non-rotary tiles
# speedup vs baseline: 1.0221x; 1.0001x over previous
.Lepi_join:
	s_andn2_b64 vcc, exec, s[6:7]
	s_mov_b64 s[0:1], -1
	s_cbranch_vccnz .LBB0_136
	s_andn2_b64 vcc, exec, s[4:5]
	s_cbranch_vccnz .LBB0_135
	s_barrier
	s_branch .LBB0_135
.Lepi_fast:
	v_lshl_or_b32 v158, s55, 8, v168
	v_ashrrev_i32_e32 v159, 31, v158
	v_mov_b64_e32 v[172:173], s[12:13]
	v_mad_i64_i32 v[172:173], s[0:1], v170, s43, v[172:173]
	v_cvt_pk_bf16_f32 v126, v126, v127
	v_cvt_pk_bf16_f32 v127, v128, v129
	v_cvt_pk_bf16_f32 v128, v122, v123
	v_cvt_pk_bf16_f32 v129, v124, v125
	v_lshl_add_u64 v[172:173], v[158:159], 1, v[172:173]
	v_cvt_pk_bf16_f32 v118, v118, v119
	v_cvt_pk_bf16_f32 v119, v120, v121
	v_cvt_pk_bf16_f32 v120, v114, v115
	v_cvt_pk_bf16_f32 v121, v116, v117
	global_store_dwordx4 v[172:173], v[126:129], off
	global_store_dwordx4 v[172:173], v[118:121], off offset:256
	v_add_u32_e32 v174, 16, v170
	v_mov_b64_e32 v[172:173], s[12:13]
	v_mad_i64_i32 v[172:173], s[0:1], v174, s43, v[172:173]
	v_cvt_pk_bf16_f32 v110, v110, v111
	v_cvt_pk_bf16_f32 v111, v112, v113
	v_cvt_pk_bf16_f32 v112, v106, v107
	v_cvt_pk_bf16_f32 v113, v108, v109
	v_lshl_add_u64 v[172:173], v[158:159], 1, v[172:173]
	v_cvt_pk_bf16_f32 v102, v102, v103
	v_cvt_pk_bf16_f32 v103, v104, v105
	v_cvt_pk_bf16_f32 v104, v98, v99
	v_cvt_pk_bf16_f32 v105, v100, v101
	global_store_dwordx4 v[172:173], v[110:113], off
	global_store_dwordx4 v[172:173], v[102:105], off offset:256
	v_add_u32_e32 v174, 32, v170
	v_mov_b64_e32 v[172:173], s[12:13]
	v_mad_i64_i32 v[172:173], s[0:1], v174, s43, v[172:173]
	v_cvt_pk_bf16_f32 v94, v94, v95
	v_cvt_pk_bf16_f32 v95, v96, v97
	v_cvt_pk_bf16_f32 v96, v90, v91
	v_cvt_pk_bf16_f32 v97, v92, v93
	v_lshl_add_u64 v[172:173], v[158:159], 1, v[172:173]
	v_cvt_pk_bf16_f32 v86, v86, v87
	v_cvt_pk_bf16_f32 v87, v88, v89
	v_cvt_pk_bf16_f32 v88, v82, v83
	v_cvt_pk_bf16_f32 v89, v84, v85
	global_store_dwordx4 v[172:173], v[94:97], off
	global_store_dwordx4 v[172:173], v[86:89], off offset:256
	v_add_u32_e32 v174, 48, v170
	v_mov_b64_e32 v[172:173], s[12:13]
	v_mad_i64_i32 v[172:173], s[0:1], v174, s43, v[172:173]
	v_cvt_pk_bf16_f32 v78, v78, v79
	v_cvt_pk_bf16_f32 v79, v80, v81
	v_cvt_pk_bf16_f32 v80, v74, v75
	v_cvt_pk_bf16_f32 v81, v76, v77
	v_lshl_add_u64 v[172:173], v[158:159], 1, v[172:173]
	v_cvt_pk_bf16_f32 v70, v70, v71
	v_cvt_pk_bf16_f32 v71, v72, v73
	v_cvt_pk_bf16_f32 v72, v66, v67
	v_cvt_pk_bf16_f32 v73, v68, v69
	global_store_dwordx4 v[172:173], v[78:81], off
	global_store_dwordx4 v[172:173], v[70:73], off offset:256
	v_add_u32_e32 v174, 0x80, v170
	v_mov_b64_e32 v[172:173], s[12:13]
	v_mad_i64_i32 v[172:173], s[0:1], v174, s43, v[172:173]
	v_cvt_pk_bf16_f32 v62, v62, v63
	v_cvt_pk_bf16_f32 v63, v64, v65
	v_cvt_pk_bf16_f32 v64, v58, v59
	v_cvt_pk_bf16_f32 v65, v60, v61
	v_lshl_add_u64 v[172:173], v[158:159], 1, v[172:173]
	v_cvt_pk_bf16_f32 v54, v54, v55
	v_cvt_pk_bf16_f32 v55, v56, v57
	v_cvt_pk_bf16_f32 v56, v50, v51
	v_cvt_pk_bf16_f32 v57, v52, v53
	global_store_dwordx4 v[172:173], v[62:65], off
	global_store_dwordx4 v[172:173], v[54:57], off offset:256
	v_add_u32_e32 v174, 0x90, v170
	v_mov_b64_e32 v[172:173], s[12:13]
	v_mad_i64_i32 v[172:173], s[0:1], v174, s43, v[172:173]
	v_cvt_pk_bf16_f32 v46, v46, v47
	v_cvt_pk_bf16_f32 v47, v48, v49
	v_cvt_pk_bf16_f32 v48, v42, v43
	v_cvt_pk_bf16_f32 v49, v44, v45
	v_lshl_add_u64 v[172:173], v[158:159], 1, v[172:173]
	v_cvt_pk_bf16_f32 v38, v38, v39
	v_cvt_pk_bf16_f32 v39, v40, v41
	v_cvt_pk_bf16_f32 v40, v34, v35
	v_cvt_pk_bf16_f32 v41, v36, v37
	global_store_dwordx4 v[172:173], v[46:49], off
	global_store_dwordx4 v[172:173], v[38:41], off offset:256
	v_add_u32_e32 v174, 0xa0, v170
	v_mov_b64_e32 v[172:173], s[12:13]
	v_mad_i64_i32 v[172:173], s[0:1], v174, s43, v[172:173]
	v_cvt_pk_bf16_f32 v30, v30, v31
	v_cvt_pk_bf16_f32 v31, v32, v33
	v_cvt_pk_bf16_f32 v32, v26, v27
	v_cvt_pk_bf16_f32 v33, v28, v29
	v_lshl_add_u64 v[172:173], v[158:159], 1, v[172:173]
	v_cvt_pk_bf16_f32 v22, v22, v23
	v_cvt_pk_bf16_f32 v23, v24, v25
	v_cvt_pk_bf16_f32 v24, v18, v19
	v_cvt_pk_bf16_f32 v25, v20, v21
	global_store_dwordx4 v[172:173], v[30:33], off
	global_store_dwordx4 v[172:173], v[22:25], off offset:256
	v_add_u32_e32 v174, 0xb0, v170
	v_mov_b64_e32 v[172:173], s[12:13]
	v_mad_i64_i32 v[172:173], s[0:1], v174, s43, v[172:173]
	v_cvt_pk_bf16_f32 v14, v14, v15
	v_cvt_pk_bf16_f32 v15, v16, v17
	v_cvt_pk_bf16_f32 v16, v10, v11
	v_cvt_pk_bf16_f32 v17, v12, v13
	v_lshl_add_u64 v[172:173], v[158:159], 1, v[172:173]
	v_cvt_pk_bf16_f32 v6, v6, v7
	v_cvt_pk_bf16_f32 v7, v8, v9
	v_cvt_pk_bf16_f32 v8, v2, v3
	v_cvt_pk_bf16_f32 v9, v4, v5
	global_store_dwordx4 v[172:173], v[14:17], off
	global_store_dwordx4 v[172:173], v[6:9], off offset:256
	s_branch .Lepi_join

.LBB0_215:
	s_or_b64 exec, exec, s[4:5]
	s_mov_b64 s[6:7], s[40:41]
	s_waitcnt lgkmcnt(0)
	s_barrier
	v_mbcnt_lo_u32_b32 v0, -1, 0
	v_mbcnt_hi_u32_b32 v0, -1, v0
	v_add_u32_e32 v2, s69, v0
	v_readlane_b32 s10, v255, 6
	v_readlane_b32 s8, v252, 8
	v_readlane_b32 s9, v252, 9
	v_readlane_b32 s12, v254, 51
	s_mul_i32 s0, s10, 0x2b98
	s_add_u32 s10, s8, s0
	s_addc_u32 s11, s9, 0
	v_lshlrev_b32_e32 v3, 2, v2
	v_add_u32_e32 v9, 0x1000, v3
	v_add_u32_e32 v10, 0x2000, v3
	v_cmp_gt_u32_e32 vcc, 230, v2
	s_nop 3
	global_load_dword v4, v3, s[10:11]
	global_load_dword v5, v3, s[10:11] offset:2048
	global_load_dword v6, v9, s[10:11]
	global_load_dword v7, v9, s[10:11] offset:2048
	global_load_dword v8, v10, s[10:11]
	s_and_saveexec_b64 s[4:5], vcc
	global_load_dword v11, v10, s[10:11] offset:2048
	s_or_b64 exec, exec, s[4:5]
	v_add_u32_e32 v3, s12, v3
	s_waitcnt vmcnt(0)
	v_mul_f32_e32 v4, 0x3fb8aa3b, v4
	v_mul_f32_e32 v5, 0x3fb8aa3b, v5
	v_mul_f32_e32 v6, 0x3fb8aa3b, v6
	v_mul_f32_e32 v7, 0x3fb8aa3b, v7
	v_mul_f32_e32 v8, 0x3fb8aa3b, v8
	ds_write_b32 v3, v4
	ds_write_b32 v3, v5 offset:2048
	ds_write_b32 v3, v6 offset:4096
	ds_write_b32 v3, v7 offset:6144
	ds_write_b32 v3, v8 offset:8192
	s_and_saveexec_b64 s[4:5], vcc
	v_mul_f32_e32 v11, 0x3fb8aa3b, v11
	ds_write_b32 v3, v11 offset:10240
